# same two-batches-in-flight unroll applied to the prepass, GU0-tail and QKV1-tail weight-transpose loops
# baseline (speedup 1.0000x reference)
.LBB0_38:
	s_lshl_b32 s8, s3, 1
	s_lshl_b32 s9, s6, 1
	v_or_b32_e32 v3, s8, v15
	v_or_b32_e32 v7, s9, v14
	s_add_i32 s10, s8, 4
	s_add_i32 s14, s9, 4
	s_add_i32 s15, s8, 8
	s_add_i32 s16, s9, 8
	s_add_i32 s17, s8, 12
	s_add_i32 s18, s9, 12
	s_add_i32 s19, s8, 16
	s_add_i32 s20, s9, 16
	s_add_i32 s21, s8, 20
	s_add_i32 s22, s9, 20
	s_add_i32 s23, s8, 24
	s_add_i32 s24, s9, 24
	s_add_i32 s8, s8, 28
	s_add_i32 s9, s9, 28
	v_add_u32_e32 v25, v7, v6
	v_or_b32_e32 v27, s10, v15
	v_or_b32_e32 v29, s14, v14
	v_or_b32_e32 v63, s15, v15
	v_or_b32_e32 v90, s16, v14
	v_or_b32_e32 v91, s17, v15
	v_or_b32_e32 v92, s18, v14
	v_or_b32_e32 v93, s19, v15
	v_or_b32_e32 v94, s20, v14
	v_or_b32_e32 v95, s21, v15
	v_or_b32_e32 v96, s22, v14
	v_or_b32_e32 v97, s23, v15
	v_or_b32_e32 v98, s24, v14
	v_or_b32_e32 v99, s8, v15
	v_or_b32_e32 v100, s9, v14
	v_add_u32_e32 v10, v3, v1
	v_mad_u64_u32 v[44:45], s[8:9], v0, v25, 0
	v_add_u32_e32 v25, v29, v6
	v_add_u32_e32 v46, v27, v1
	v_add_u32_e32 v68, v90, v6
	v_add_u32_e32 v66, v63, v1
	v_add_u32_e32 v72, v92, v6
	v_add_u32_e32 v70, v91, v1
	v_add_u32_e32 v76, v94, v6
	v_add_u32_e32 v74, v93, v1
	v_add_u32_e32 v80, v96, v6
	v_add_u32_e32 v78, v95, v1
	v_add_u32_e32 v84, v98, v6
	v_add_u32_e32 v82, v97, v1
	v_add_u32_e32 v88, v100, v6
	v_add_u32_e32 v86, v99, v1
	v_mad_u64_u32 v[10:11], s[8:9], v2, v10, 0
	v_lshl_add_u64 v[44:45], v[44:45], 2, v[8:9]
	v_mad_u64_u32 v[46:47], s[8:9], v2, v46, 0
	v_mad_u64_u32 v[64:65], s[8:9], v0, v25, 0
	v_mad_u64_u32 v[66:67], s[8:9], v2, v66, 0
	v_mad_u64_u32 v[68:69], s[8:9], v0, v68, 0
	v_mad_u64_u32 v[70:71], s[8:9], v2, v70, 0
	v_mad_u64_u32 v[72:73], s[8:9], v0, v72, 0
	v_mad_u64_u32 v[74:75], s[8:9], v2, v74, 0
	v_mad_u64_u32 v[76:77], s[8:9], v0, v76, 0
	v_mad_u64_u32 v[78:79], s[8:9], v2, v78, 0
	v_mad_u64_u32 v[80:81], s[8:9], v0, v80, 0
	v_mad_u64_u32 v[82:83], s[8:9], v2, v82, 0
	v_mad_u64_u32 v[84:85], s[8:9], v0, v84, 0
	v_mad_u64_u32 v[86:87], s[8:9], v2, v86, 0
	v_mad_u64_u32 v[88:89], s[8:9], v0, v88, 0
	v_lshl_add_u64 v[10:11], v[10:11], 2, v[8:9]
	v_lshl_add_u64 v[64:65], v[64:65], 2, v[8:9]
	v_lshl_add_u64 v[46:47], v[46:47], 2, v[8:9]
	v_lshl_add_u64 v[68:69], v[68:69], 2, v[8:9]
	v_lshl_add_u64 v[66:67], v[66:67], 2, v[8:9]
	v_lshl_add_u64 v[72:73], v[72:73], 2, v[8:9]
	v_lshl_add_u64 v[70:71], v[70:71], 2, v[8:9]
	v_lshl_add_u64 v[76:77], v[76:77], 2, v[8:9]
	v_lshl_add_u64 v[74:75], v[74:75], 2, v[8:9]
	v_lshl_add_u64 v[80:81], v[80:81], 2, v[8:9]
	v_lshl_add_u64 v[78:79], v[78:79], 2, v[8:9]
	v_lshl_add_u64 v[84:85], v[84:85], 2, v[8:9]
	v_lshl_add_u64 v[82:83], v[82:83], 2, v[8:9]
	v_lshl_add_u64 v[88:89], v[88:89], 2, v[8:9]
	v_lshl_add_u64 v[86:87], v[86:87], 2, v[8:9]
	global_load_dword v25, v[44:45], off nt
	global_load_dword v101, v[10:11], off nt
	global_load_dword v102, v[64:65], off nt
	global_load_dword v103, v[46:47], off nt
	global_load_dword v104, v[68:69], off nt
	global_load_dword v105, v[66:67], off nt
	global_load_dword v106, v[72:73], off nt
	global_load_dword v107, v[70:71], off nt
	global_load_dword v108, v[76:77], off nt
	global_load_dword v109, v[74:75], off nt
	global_load_dword v110, v[80:81], off nt
	global_load_dword v111, v[78:79], off nt
	global_load_dword v112, v[84:85], off nt
	global_load_dword v113, v[82:83], off nt
	global_load_dword v114, v[88:89], off nt
	global_load_dword v115, v[86:87], off nt
	s_add_i32 s6, s6, 16
	s_add_i32 s3, s3, 16
	v_mad_u64_u32 v[10:11], s[8:9], v7, s0, v[16:17]
	v_mad_u64_u32 v[44:45], s[8:9], v3, s0, v[16:17]
	v_mad_u64_u32 v[46:47], s[8:9], v29, s0, v[16:17]
	v_mad_u64_u32 v[64:65], s[8:9], v27, s0, v[16:17]
	v_mad_u64_u32 v[66:67], s[8:9], v90, s0, v[16:17]
	v_mad_u64_u32 v[68:69], s[8:9], v63, s0, v[16:17]
	v_mad_u64_u32 v[70:71], s[8:9], v92, s0, v[16:17]
	v_mad_u64_u32 v[72:73], s[8:9], v91, s0, v[16:17]
	v_mad_u64_u32 v[74:75], s[8:9], v94, s0, v[16:17]
	v_mad_u64_u32 v[76:77], s[8:9], v93, s0, v[16:17]
	v_mad_u64_u32 v[78:79], s[8:9], v96, s0, v[16:17]
	v_mad_u64_u32 v[80:81], s[8:9], v95, s0, v[16:17]
	v_mad_u64_u32 v[82:83], s[8:9], v98, s0, v[16:17]
	v_mad_u64_u32 v[84:85], s[8:9], v97, s0, v[16:17]
	v_mad_u64_u32 v[86:87], s[8:9], v100, s0, v[16:17]
	v_mad_u64_u32 v[88:89], s[8:9], v99, s0, v[16:17]
	s_lshl_b32 s8, s3, 1
	s_lshl_b32 s9, s6, 1
	v_or_b32_e32 v3, s8, v15
	v_or_b32_e32 v7, s9, v14
	s_add_i32 s10, s8, 4
	s_add_i32 s14, s9, 4
	s_add_i32 s15, s8, 8
	s_add_i32 s16, s9, 8
	s_add_i32 s17, s8, 12
	s_add_i32 s18, s9, 12
	s_add_i32 s19, s8, 16
	s_add_i32 s20, s9, 16
	s_add_i32 s21, s8, 20
	s_add_i32 s22, s9, 20
	s_add_i32 s23, s8, 24
	s_add_i32 s24, s9, 24
	s_add_i32 s8, s8, 28
	s_add_i32 s9, s9, 28
	v_add_u32_e32 v130, v7, v6
	v_or_b32_e32 v27, s10, v15
	v_or_b32_e32 v29, s14, v14
	v_or_b32_e32 v63, s15, v15
	v_or_b32_e32 v90, s16, v14
	v_or_b32_e32 v91, s17, v15
	v_or_b32_e32 v92, s18, v14
	v_or_b32_e32 v93, s19, v15
	v_or_b32_e32 v94, s20, v14
	v_or_b32_e32 v95, s21, v15
	v_or_b32_e32 v96, s22, v14
	v_or_b32_e32 v97, s23, v15
	v_or_b32_e32 v98, s24, v14
	v_or_b32_e32 v99, s8, v15
	v_or_b32_e32 v100, s9, v14
	v_add_u32_e32 v186, v3, v1
	v_mad_u64_u32 v[188:189], s[8:9], v0, v130, 0
	v_add_u32_e32 v130, v29, v6
	v_add_u32_e32 v190, v27, v1
	v_add_u32_e32 v196, v90, v6
	v_add_u32_e32 v194, v63, v1
	v_add_u32_e32 v200, v92, v6
	v_add_u32_e32 v198, v91, v1
	v_add_u32_e32 v204, v94, v6
	v_add_u32_e32 v202, v93, v1
	v_add_u32_e32 v208, v96, v6
	v_add_u32_e32 v206, v95, v1
	v_add_u32_e32 v212, v98, v6
	v_add_u32_e32 v210, v97, v1
	v_add_u32_e32 v216, v100, v6
	v_add_u32_e32 v214, v99, v1
	v_mad_u64_u32 v[186:187], s[8:9], v2, v186, 0
	v_lshl_add_u64 v[188:189], v[188:189], 2, v[8:9]
	v_mad_u64_u32 v[190:191], s[8:9], v2, v190, 0
	v_mad_u64_u32 v[192:193], s[8:9], v0, v130, 0
	v_mad_u64_u32 v[194:195], s[8:9], v2, v194, 0
	v_mad_u64_u32 v[196:197], s[8:9], v0, v196, 0
	v_mad_u64_u32 v[198:199], s[8:9], v2, v198, 0
	v_mad_u64_u32 v[200:201], s[8:9], v0, v200, 0
	v_mad_u64_u32 v[202:203], s[8:9], v2, v202, 0
	v_mad_u64_u32 v[204:205], s[8:9], v0, v204, 0
	v_mad_u64_u32 v[206:207], s[8:9], v2, v206, 0
	v_mad_u64_u32 v[208:209], s[8:9], v0, v208, 0
	v_mad_u64_u32 v[210:211], s[8:9], v2, v210, 0
	v_mad_u64_u32 v[212:213], s[8:9], v0, v212, 0
	v_mad_u64_u32 v[214:215], s[8:9], v2, v214, 0
	v_mad_u64_u32 v[216:217], s[8:9], v0, v216, 0
	v_lshl_add_u64 v[186:187], v[186:187], 2, v[8:9]
	v_lshl_add_u64 v[192:193], v[192:193], 2, v[8:9]
	v_lshl_add_u64 v[190:191], v[190:191], 2, v[8:9]
	v_lshl_add_u64 v[196:197], v[196:197], 2, v[8:9]
	v_lshl_add_u64 v[194:195], v[194:195], 2, v[8:9]
	v_lshl_add_u64 v[200:201], v[200:201], 2, v[8:9]
	v_lshl_add_u64 v[198:199], v[198:199], 2, v[8:9]
	v_lshl_add_u64 v[204:205], v[204:205], 2, v[8:9]
	v_lshl_add_u64 v[202:203], v[202:203], 2, v[8:9]
	v_lshl_add_u64 v[208:209], v[208:209], 2, v[8:9]
	v_lshl_add_u64 v[206:207], v[206:207], 2, v[8:9]
	v_lshl_add_u64 v[212:213], v[212:213], 2, v[8:9]
	v_lshl_add_u64 v[210:211], v[210:211], 2, v[8:9]
	v_lshl_add_u64 v[216:217], v[216:217], 2, v[8:9]
	v_lshl_add_u64 v[214:215], v[214:215], 2, v[8:9]
	global_load_dword v130, v[188:189], off nt
	global_load_dword v131, v[186:187], off nt
	global_load_dword v132, v[192:193], off nt
	global_load_dword v133, v[190:191], off nt
	global_load_dword v134, v[196:197], off nt
	global_load_dword v135, v[194:195], off nt
	global_load_dword v136, v[200:201], off nt
	global_load_dword v137, v[198:199], off nt
	global_load_dword v138, v[204:205], off nt
	global_load_dword v139, v[202:203], off nt
	global_load_dword v140, v[208:209], off nt
	global_load_dword v141, v[206:207], off nt
	global_load_dword v142, v[212:213], off nt
	global_load_dword v143, v[210:211], off nt
	global_load_dword v150, v[216:217], off nt
	global_load_dword v151, v[214:215], off nt
	s_add_i32 s6, s6, 16
	s_add_i32 s3, s3, 16
	s_mov_b32 s7, 0
	v_mad_u64_u32 v[186:187], s[8:9], v7, s0, v[16:17]
	v_mad_u64_u32 v[188:189], s[8:9], v3, s0, v[16:17]
	v_mad_u64_u32 v[190:191], s[8:9], v29, s0, v[16:17]
	v_mad_u64_u32 v[192:193], s[8:9], v27, s0, v[16:17]
	v_mad_u64_u32 v[194:195], s[8:9], v90, s0, v[16:17]
	v_mad_u64_u32 v[196:197], s[8:9], v63, s0, v[16:17]
	v_mad_u64_u32 v[198:199], s[8:9], v92, s0, v[16:17]
	v_mad_u64_u32 v[200:201], s[8:9], v91, s0, v[16:17]
	v_mad_u64_u32 v[202:203], s[8:9], v94, s0, v[16:17]
	v_mad_u64_u32 v[204:205], s[8:9], v93, s0, v[16:17]
	v_mad_u64_u32 v[206:207], s[8:9], v96, s0, v[16:17]
	v_mad_u64_u32 v[208:209], s[8:9], v95, s0, v[16:17]
	v_mad_u64_u32 v[210:211], s[8:9], v98, s0, v[16:17]
	v_mad_u64_u32 v[212:213], s[8:9], v97, s0, v[16:17]
	v_mad_u64_u32 v[214:215], s[8:9], v100, s0, v[16:17]
	v_mad_u64_u32 v[216:217], s[8:9], v99, s0, v[16:17]
	s_waitcnt vmcnt(31)
	ds_write_b32 v10, v25
	s_waitcnt vmcnt(30)
	ds_write_b32 v44, v101
	s_waitcnt vmcnt(29)
	ds_write_b32 v46, v102
	s_waitcnt vmcnt(28)
	ds_write_b32 v64, v103
	s_waitcnt vmcnt(27)
	ds_write_b32 v66, v104
	s_waitcnt vmcnt(26)
	ds_write_b32 v68, v105
	s_waitcnt vmcnt(25)
	ds_write_b32 v70, v106
	s_waitcnt vmcnt(24)
	ds_write_b32 v72, v107
	s_waitcnt vmcnt(23)
	ds_write_b32 v74, v108
	s_waitcnt vmcnt(22)
	ds_write_b32 v76, v109
	s_waitcnt vmcnt(21)
	ds_write_b32 v78, v110
	s_waitcnt vmcnt(20)
	ds_write_b32 v80, v111
	s_waitcnt vmcnt(19)
	ds_write_b32 v82, v112
	s_waitcnt vmcnt(18)
	ds_write_b32 v84, v113
	s_waitcnt vmcnt(17)
	ds_write_b32 v86, v114
	s_waitcnt vmcnt(16)
	ds_write_b32 v88, v115
	s_waitcnt vmcnt(15)
	ds_write_b32 v186, v130
	s_waitcnt vmcnt(14)
	ds_write_b32 v188, v131
	s_waitcnt vmcnt(13)
	ds_write_b32 v190, v132
	s_waitcnt vmcnt(12)
	ds_write_b32 v192, v133
	s_waitcnt vmcnt(11)
	ds_write_b32 v194, v134
	s_waitcnt vmcnt(10)
	ds_write_b32 v196, v135
	s_waitcnt vmcnt(9)
	ds_write_b32 v198, v136
	s_waitcnt vmcnt(8)
	ds_write_b32 v200, v137
	s_waitcnt vmcnt(7)
	ds_write_b32 v202, v138
	s_waitcnt vmcnt(6)
	ds_write_b32 v204, v139
	s_waitcnt vmcnt(5)
	ds_write_b32 v206, v140
	s_waitcnt vmcnt(4)
	ds_write_b32 v208, v141
	s_waitcnt vmcnt(3)
	ds_write_b32 v210, v142
	s_waitcnt vmcnt(2)
	ds_write_b32 v212, v143
	s_waitcnt vmcnt(1)
	ds_write_b32 v214, v150
	s_waitcnt vmcnt(0)
	ds_write_b32 v216, v151
	s_waitcnt lgkmcnt(0)
	v_lshl_add_u64 v[0:1], s[56:57], 0, v[4:5]
	v_lshlrev_b32_e32 v2, 1, v6
	ds_read2_b32 v[4:5], v49 offset0:33 offset1:41
	ds_read2_b32 v[6:7], v49 offset1:8
	ds_read2_b32 v[8:9], v49 offset0:66 offset1:74
	ds_read2_b32 v[10:11], v49 offset0:99 offset1:107
	ds_read2_b32 v[44:45], v49 offset0:132 offset1:140
	ds_read2_b32 v[46:47], v49 offset0:165 offset1:173
	ds_read2_b32 v[64:65], v49 offset0:198 offset1:206
	ds_read2_b32 v[66:67], v49 offset0:231 offset1:239
	v_mov_b32_e32 v3, v13
	v_lshl_add_u64 v[0:1], v[0:1], 0, v[2:3]
	v_mov_b32_e32 v27, v13
	v_or_b32_e32 v70, v12, v48
	v_mov_b32_e32 v71, v13
	v_lshl_add_u64 v[68:69], v[0:1], 0, v[26:27]
	v_lshlrev_b64 v[70:71], 11, v[70:71]
	s_waitcnt lgkmcnt(6)
	v_cvt_pk_bf16_f32 v0, v6, v4
	s_waitcnt lgkmcnt(4)
	v_cvt_pk_bf16_f32 v1, v8, v10
	s_waitcnt lgkmcnt(2)
	v_cvt_pk_bf16_f32 v2, v44, v46
	s_waitcnt lgkmcnt(0)
	v_cvt_pk_bf16_f32 v3, v64, v66
	v_lshl_add_u64 v[70:71], v[68:69], 0, v[70:71]
	global_store_dwordx4 v[70:71], v[0:3], off sc1
	v_or_b32_e32 v4, v12, v50
	s_mov_b64 s[6:7], 0
	v_cvt_pk_bf16_f32 v0, v7, v5
	v_cvt_pk_bf16_f32 v1, v9, v11
	v_cvt_pk_bf16_f32 v2, v45, v47
	v_cvt_pk_bf16_f32 v3, v65, v67
	v_mov_b32_e32 v5, v13
	ds_read2_b32 v[6:7], v49 offset0:49 offset1:57
	ds_read2_b32 v[8:9], v49 offset0:16 offset1:24
	ds_read2_b32 v[10:11], v49 offset0:82 offset1:90
	ds_read2_b32 v[44:45], v49 offset0:115 offset1:123
	ds_read2_b32 v[46:47], v49 offset0:148 offset1:156
	ds_read2_b32 v[64:65], v49 offset0:181 offset1:189
	ds_read2_b32 v[66:67], v49 offset0:214 offset1:222
	ds_read2_b32 v[70:71], v49 offset0:247 offset1:255
	v_lshlrev_b64 v[4:5], 11, v[4:5]
	v_lshl_add_u64 v[4:5], v[68:69], 0, v[4:5]
	global_store_dwordx4 v[4:5], v[0:3], off sc1
	v_or_b32_e32 v4, v12, v51
	v_mov_b32_e32 v5, v13
	v_lshlrev_b64 v[4:5], 11, v[4:5]
	s_waitcnt lgkmcnt(6)
	v_cvt_pk_bf16_f32 v0, v8, v6
	s_waitcnt lgkmcnt(4)
	v_cvt_pk_bf16_f32 v1, v10, v44
	s_waitcnt lgkmcnt(2)
	v_cvt_pk_bf16_f32 v2, v46, v64
	s_waitcnt lgkmcnt(0)
	v_cvt_pk_bf16_f32 v3, v66, v70
	v_lshl_add_u64 v[4:5], v[68:69], 0, v[4:5]
	v_or_b32_e32 v12, v12, v52
	global_store_dwordx4 v[4:5], v[0:3], off sc1
	v_lshlrev_b64 v[4:5], 11, v[12:13]
	v_lshl_add_u64 v[4:5], v[68:69], 0, v[4:5]
	v_cvt_pk_bf16_f32 v0, v9, v7
	v_cvt_pk_bf16_f32 v1, v11, v45
	v_cvt_pk_bf16_f32 v2, v47, v65
	v_cvt_pk_bf16_f32 v3, v67, v71
	global_store_dwordx4 v[4:5], v[0:3], off sc1
	s_waitcnt lgkmcnt(0)

.Lgu0h_BB0_1032:
	s_lshl_b32 s8, s6, 1
	s_lshl_b32 s9, s5, 1
	v_or_b32_e32 v9, s8, v1
	v_or_b32_e32 v11, s9, v0
	s_add_i32 s10, s8, 4
	s_add_i32 s11, s9, 4
	s_add_i32 s12, s8, 8
	s_add_i32 s13, s9, 8
	s_add_i32 s14, s8, 12
	s_add_i32 s15, s9, 12
	s_add_i32 s16, s8, 16
	s_add_i32 s17, s9, 16
	s_add_i32 s18, s8, 20
	s_add_i32 s19, s9, 20
	s_add_i32 s20, s8, 24
	s_add_i32 s21, s9, 24
	s_add_i32 s8, s8, 28
	s_add_i32 s9, s9, 28
	v_add_u32_e32 v17, v9, v7
	v_add_u32_e32 v37, v11, v16
	v_or_b32_e32 v70, s10, v1
	v_or_b32_e32 v71, s11, v0
	v_or_b32_e32 v72, s12, v1
	v_or_b32_e32 v73, s13, v0
	v_or_b32_e32 v74, s14, v1
	v_or_b32_e32 v75, s15, v0
	v_or_b32_e32 v76, s16, v1
	v_or_b32_e32 v77, s17, v0
	v_or_b32_e32 v78, s18, v1
	v_or_b32_e32 v79, s19, v0
	v_or_b32_e32 v80, s20, v1
	v_or_b32_e32 v81, s21, v0
	v_or_b32_e32 v82, s8, v1
	v_or_b32_e32 v83, s9, v0
	v_ashrrev_i32_e32 v42, 31, v37
	v_ashrrev_i32_e32 v43, 31, v17
	v_mul_lo_u32 v84, v3, v17
	v_mad_u64_u32 v[38:39], s[8:9], v2, v17, 0
	v_mul_lo_u32 v17, v13, v37
	v_mad_u64_u32 v[40:41], s[8:9], v12, v37, 0
	v_add_u32_e32 v37, v70, v7
	v_add_u32_e32 v44, v71, v16
	v_add_u32_e32 v46, v72, v7
	v_add_u32_e32 v48, v73, v16
	v_add_u32_e32 v50, v74, v7
	v_add_u32_e32 v52, v75, v16
	v_add_u32_e32 v54, v76, v7
	v_add_u32_e32 v56, v77, v16
	v_add_u32_e32 v58, v78, v7
	v_add_u32_e32 v60, v79, v16
	v_add_u32_e32 v62, v80, v7
	v_add_u32_e32 v64, v81, v16
	v_add_u32_e32 v66, v82, v7
	v_add_u32_e32 v68, v83, v16
	v_mul_lo_u32 v85, v2, v43
	v_mul_lo_u32 v86, v12, v42
	v_ashrrev_i32_e32 v87, 31, v44
	v_ashrrev_i32_e32 v88, 31, v37
	v_ashrrev_i32_e32 v90, 31, v48
	v_ashrrev_i32_e32 v91, 31, v46
	v_ashrrev_i32_e32 v94, 31, v52
	v_ashrrev_i32_e32 v95, 31, v50
	v_ashrrev_i32_e32 v98, 31, v56
	v_ashrrev_i32_e32 v99, 31, v54
	v_ashrrev_i32_e32 v102, 31, v60
	v_ashrrev_i32_e32 v103, 31, v58
	v_ashrrev_i32_e32 v106, 31, v64
	v_ashrrev_i32_e32 v107, 31, v62
	v_ashrrev_i32_e32 v110, 31, v68
	v_ashrrev_i32_e32 v111, 31, v66
	v_mul_lo_u32 v89, v3, v37
	v_mad_u64_u32 v[42:43], s[8:9], v2, v37, 0
	v_mul_lo_u32 v37, v13, v44
	v_mad_u64_u32 v[44:45], s[8:9], v12, v44, 0
	v_mul_lo_u32 v92, v3, v46
	v_mad_u64_u32 v[46:47], s[8:9], v2, v46, 0
	v_mul_lo_u32 v93, v13, v48
	v_mad_u64_u32 v[48:49], s[8:9], v12, v48, 0
	v_mul_lo_u32 v96, v3, v50
	v_mad_u64_u32 v[50:51], s[8:9], v2, v50, 0
	v_mul_lo_u32 v97, v13, v52
	v_mad_u64_u32 v[52:53], s[8:9], v12, v52, 0
	v_mul_lo_u32 v100, v3, v54
	v_mad_u64_u32 v[54:55], s[8:9], v2, v54, 0
	v_mul_lo_u32 v101, v13, v56
	v_mad_u64_u32 v[56:57], s[8:9], v12, v56, 0
	v_mul_lo_u32 v104, v3, v58
	v_mad_u64_u32 v[58:59], s[8:9], v2, v58, 0
	v_mul_lo_u32 v105, v13, v60
	v_mad_u64_u32 v[60:61], s[8:9], v12, v60, 0
	v_mul_lo_u32 v108, v3, v62
	v_mad_u64_u32 v[62:63], s[8:9], v2, v62, 0
	v_mul_lo_u32 v109, v13, v64
	v_mad_u64_u32 v[64:65], s[8:9], v12, v64, 0
	v_mul_lo_u32 v112, v3, v66
	v_mad_u64_u32 v[66:67], s[8:9], v2, v66, 0
	v_mul_lo_u32 v113, v13, v68
	v_mad_u64_u32 v[68:69], s[8:9], v12, v68, 0
	v_add3_u32 v39, v39, v85, v84
	v_add3_u32 v41, v41, v86, v17
	v_mul_lo_u32 v17, v2, v88
	v_mul_lo_u32 v84, v12, v87
	v_mul_lo_u32 v85, v2, v91
	v_mul_lo_u32 v86, v12, v90
	v_mul_lo_u32 v87, v2, v95
	v_mul_lo_u32 v88, v12, v94
	v_mul_lo_u32 v90, v2, v99
	v_mul_lo_u32 v91, v12, v98
	v_mul_lo_u32 v94, v2, v103
	v_mul_lo_u32 v95, v12, v102
	v_mul_lo_u32 v98, v2, v107
	v_mul_lo_u32 v99, v12, v106
	v_mul_lo_u32 v102, v2, v111
	v_mul_lo_u32 v103, v12, v110
	v_lshl_add_u64 v[40:41], v[40:41], 2, v[18:19]
	v_add3_u32 v43, v43, v17, v89
	v_add3_u32 v45, v45, v84, v37
	v_add3_u32 v47, v47, v85, v92
	v_add3_u32 v49, v49, v86, v93
	v_add3_u32 v51, v51, v87, v96
	v_add3_u32 v53, v53, v88, v97
	v_add3_u32 v55, v55, v90, v100
	v_add3_u32 v57, v57, v91, v101
	v_add3_u32 v59, v59, v94, v104
	v_add3_u32 v61, v61, v95, v105
	v_add3_u32 v63, v63, v98, v108
	v_add3_u32 v65, v65, v99, v109
	v_add3_u32 v67, v67, v102, v112
	v_add3_u32 v69, v69, v103, v113
	v_lshl_add_u64 v[38:39], v[38:39], 2, v[18:19]
	v_lshl_add_u64 v[44:45], v[44:45], 2, v[18:19]
	v_lshl_add_u64 v[42:43], v[42:43], 2, v[18:19]
	v_lshl_add_u64 v[48:49], v[48:49], 2, v[18:19]
	v_lshl_add_u64 v[46:47], v[46:47], 2, v[18:19]
	v_lshl_add_u64 v[52:53], v[52:53], 2, v[18:19]
	v_lshl_add_u64 v[50:51], v[50:51], 2, v[18:19]
	v_lshl_add_u64 v[56:57], v[56:57], 2, v[18:19]
	v_lshl_add_u64 v[54:55], v[54:55], 2, v[18:19]
	v_lshl_add_u64 v[60:61], v[60:61], 2, v[18:19]
	v_lshl_add_u64 v[58:59], v[58:59], 2, v[18:19]
	v_lshl_add_u64 v[64:65], v[64:65], 2, v[18:19]
	v_lshl_add_u64 v[62:63], v[62:63], 2, v[18:19]
	v_lshl_add_u64 v[68:69], v[68:69], 2, v[18:19]
	v_lshl_add_u64 v[66:67], v[66:67], 2, v[18:19]
	global_load_dword v17, v[40:41], off nt
	global_load_dword v37, v[38:39], off nt
	global_load_dword v84, v[44:45], off nt
	global_load_dword v85, v[42:43], off nt
	global_load_dword v86, v[48:49], off nt
	global_load_dword v87, v[46:47], off nt
	global_load_dword v88, v[52:53], off nt
	global_load_dword v89, v[50:51], off nt
	global_load_dword v90, v[56:57], off nt
	global_load_dword v91, v[54:55], off nt
	global_load_dword v92, v[60:61], off nt
	global_load_dword v93, v[58:59], off nt
	global_load_dword v94, v[64:65], off nt
	global_load_dword v95, v[62:63], off nt
	global_load_dword v96, v[68:69], off nt
	global_load_dword v97, v[66:67], off nt
	s_add_i32 s5, s5, 16
	s_add_i32 s6, s6, 16
	v_mad_u64_u32 v[38:39], s[8:9], v11, s1, v[6:7]
	v_mad_u64_u32 v[40:41], s[8:9], v9, s1, v[6:7]
	v_mad_u64_u32 v[42:43], s[8:9], v71, s1, v[6:7]
	v_mad_u64_u32 v[44:45], s[8:9], v70, s1, v[6:7]
	v_mad_u64_u32 v[46:47], s[8:9], v73, s1, v[6:7]
	v_mad_u64_u32 v[48:49], s[8:9], v72, s1, v[6:7]
	v_mad_u64_u32 v[50:51], s[8:9], v75, s1, v[6:7]
	v_mad_u64_u32 v[52:53], s[8:9], v74, s1, v[6:7]
	v_mad_u64_u32 v[54:55], s[8:9], v77, s1, v[6:7]
	v_mad_u64_u32 v[56:57], s[8:9], v76, s1, v[6:7]
	v_mad_u64_u32 v[58:59], s[8:9], v79, s1, v[6:7]
	v_mad_u64_u32 v[60:61], s[8:9], v78, s1, v[6:7]
	v_mad_u64_u32 v[62:63], s[8:9], v81, s1, v[6:7]
	v_mad_u64_u32 v[64:65], s[8:9], v80, s1, v[6:7]
	v_mad_u64_u32 v[66:67], s[8:9], v83, s1, v[6:7]
	v_mad_u64_u32 v[68:69], s[8:9], v82, s1, v[6:7]
	s_lshl_b32 s8, s6, 1
	s_lshl_b32 s9, s5, 1
	v_or_b32_e32 v9, s8, v1
	v_or_b32_e32 v11, s9, v0
	s_add_i32 s10, s8, 4
	s_add_i32 s11, s9, 4
	s_add_i32 s12, s8, 8
	s_add_i32 s13, s9, 8
	s_add_i32 s14, s8, 12
	s_add_i32 s15, s9, 12
	s_add_i32 s16, s8, 16
	s_add_i32 s17, s9, 16
	s_add_i32 s18, s8, 20
	s_add_i32 s19, s9, 20
	s_add_i32 s20, s8, 24
	s_add_i32 s21, s9, 24
	s_add_i32 s8, s8, 28
	s_add_i32 s9, s9, 28
	v_add_u32_e32 v120, v9, v7
	v_add_u32_e32 v121, v11, v16
	v_or_b32_e32 v70, s10, v1
	v_or_b32_e32 v71, s11, v0
	v_or_b32_e32 v72, s12, v1
	v_or_b32_e32 v73, s13, v0
	v_or_b32_e32 v74, s14, v1
	v_or_b32_e32 v75, s15, v0
	v_or_b32_e32 v76, s16, v1
	v_or_b32_e32 v77, s17, v0
	v_or_b32_e32 v78, s18, v1
	v_or_b32_e32 v79, s19, v0
	v_or_b32_e32 v80, s20, v1
	v_or_b32_e32 v81, s21, v0
	v_or_b32_e32 v82, s8, v1
	v_or_b32_e32 v83, s9, v0
	v_ashrrev_i32_e32 v190, 31, v121
	v_ashrrev_i32_e32 v191, 31, v120
	v_mul_lo_u32 v122, v3, v120
	v_mad_u64_u32 v[186:187], s[8:9], v2, v120, 0
	v_mul_lo_u32 v120, v13, v121
	v_mad_u64_u32 v[188:189], s[8:9], v12, v121, 0
	v_add_u32_e32 v121, v70, v7
	v_add_u32_e32 v192, v71, v16
	v_add_u32_e32 v194, v72, v7
	v_add_u32_e32 v196, v73, v16
	v_add_u32_e32 v198, v74, v7
	v_add_u32_e32 v200, v75, v16
	v_add_u32_e32 v202, v76, v7
	v_add_u32_e32 v204, v77, v16
	v_add_u32_e32 v206, v78, v7
	v_add_u32_e32 v208, v79, v16
	v_add_u32_e32 v210, v80, v7
	v_add_u32_e32 v212, v81, v16
	v_add_u32_e32 v214, v82, v7
	v_add_u32_e32 v216, v83, v16
	v_mul_lo_u32 v123, v2, v191
	v_mul_lo_u32 v124, v12, v190
	v_ashrrev_i32_e32 v125, 31, v192
	v_ashrrev_i32_e32 v126, 31, v121
	v_ashrrev_i32_e32 v128, 31, v196
	v_ashrrev_i32_e32 v129, 31, v194
	v_ashrrev_i32_e32 v132, 31, v200
	v_ashrrev_i32_e32 v133, 31, v198
	v_ashrrev_i32_e32 v98, 31, v204
	v_ashrrev_i32_e32 v99, 31, v202
	v_ashrrev_i32_e32 v102, 31, v208
	v_ashrrev_i32_e32 v103, 31, v206
	v_ashrrev_i32_e32 v106, 31, v212
	v_ashrrev_i32_e32 v107, 31, v210
	v_ashrrev_i32_e32 v110, 31, v216
	v_ashrrev_i32_e32 v111, 31, v214
	v_mul_lo_u32 v127, v3, v121
	v_mad_u64_u32 v[190:191], s[8:9], v2, v121, 0
	v_mul_lo_u32 v121, v13, v192
	v_mad_u64_u32 v[192:193], s[8:9], v12, v192, 0
	v_mul_lo_u32 v130, v3, v194
	v_mad_u64_u32 v[194:195], s[8:9], v2, v194, 0
	v_mul_lo_u32 v131, v13, v196
	v_mad_u64_u32 v[196:197], s[8:9], v12, v196, 0
	v_mul_lo_u32 v134, v3, v198
	v_mad_u64_u32 v[198:199], s[8:9], v2, v198, 0
	v_mul_lo_u32 v135, v13, v200
	v_mad_u64_u32 v[200:201], s[8:9], v12, v200, 0
	v_mul_lo_u32 v100, v3, v202
	v_mad_u64_u32 v[202:203], s[8:9], v2, v202, 0
	v_mul_lo_u32 v101, v13, v204
	v_mad_u64_u32 v[204:205], s[8:9], v12, v204, 0
	v_mul_lo_u32 v104, v3, v206
	v_mad_u64_u32 v[206:207], s[8:9], v2, v206, 0
	v_mul_lo_u32 v105, v13, v208
	v_mad_u64_u32 v[208:209], s[8:9], v12, v208, 0
	v_mul_lo_u32 v108, v3, v210
	v_mad_u64_u32 v[210:211], s[8:9], v2, v210, 0
	v_mul_lo_u32 v109, v13, v212
	v_mad_u64_u32 v[212:213], s[8:9], v12, v212, 0
	v_mul_lo_u32 v112, v3, v214
	v_mad_u64_u32 v[214:215], s[8:9], v2, v214, 0
	v_mul_lo_u32 v113, v13, v216
	v_mad_u64_u32 v[216:217], s[8:9], v12, v216, 0
	v_add3_u32 v187, v187, v123, v122
	v_add3_u32 v189, v189, v124, v120
	v_mul_lo_u32 v120, v2, v126
	v_mul_lo_u32 v122, v12, v125
	v_mul_lo_u32 v123, v2, v129
	v_mul_lo_u32 v124, v12, v128
	v_mul_lo_u32 v125, v2, v133
	v_mul_lo_u32 v126, v12, v132
	v_mul_lo_u32 v128, v2, v99
	v_mul_lo_u32 v129, v12, v98
	v_mul_lo_u32 v132, v2, v103
	v_mul_lo_u32 v133, v12, v102
	v_mul_lo_u32 v98, v2, v107
	v_mul_lo_u32 v99, v12, v106
	v_mul_lo_u32 v102, v2, v111
	v_mul_lo_u32 v103, v12, v110
	v_lshl_add_u64 v[188:189], v[188:189], 2, v[18:19]
	v_add3_u32 v191, v191, v120, v127
	v_add3_u32 v193, v193, v122, v121
	v_add3_u32 v195, v195, v123, v130
	v_add3_u32 v197, v197, v124, v131
	v_add3_u32 v199, v199, v125, v134
	v_add3_u32 v201, v201, v126, v135
	v_add3_u32 v203, v203, v128, v100
	v_add3_u32 v205, v205, v129, v101
	v_add3_u32 v207, v207, v132, v104
	v_add3_u32 v209, v209, v133, v105
	v_add3_u32 v211, v211, v98, v108
	v_add3_u32 v213, v213, v99, v109
	v_add3_u32 v215, v215, v102, v112
	v_add3_u32 v217, v217, v103, v113
	v_lshl_add_u64 v[186:187], v[186:187], 2, v[18:19]
	v_lshl_add_u64 v[192:193], v[192:193], 2, v[18:19]
	v_lshl_add_u64 v[190:191], v[190:191], 2, v[18:19]
	v_lshl_add_u64 v[196:197], v[196:197], 2, v[18:19]
	v_lshl_add_u64 v[194:195], v[194:195], 2, v[18:19]
	v_lshl_add_u64 v[200:201], v[200:201], 2, v[18:19]
	v_lshl_add_u64 v[198:199], v[198:199], 2, v[18:19]
	v_lshl_add_u64 v[204:205], v[204:205], 2, v[18:19]
	v_lshl_add_u64 v[202:203], v[202:203], 2, v[18:19]
	v_lshl_add_u64 v[208:209], v[208:209], 2, v[18:19]
	v_lshl_add_u64 v[206:207], v[206:207], 2, v[18:19]
	v_lshl_add_u64 v[212:213], v[212:213], 2, v[18:19]
	v_lshl_add_u64 v[210:211], v[210:211], 2, v[18:19]
	v_lshl_add_u64 v[216:217], v[216:217], 2, v[18:19]
	v_lshl_add_u64 v[214:215], v[214:215], 2, v[18:19]
	global_load_dword v120, v[188:189], off nt
	global_load_dword v121, v[186:187], off nt
	global_load_dword v122, v[192:193], off nt
	global_load_dword v123, v[190:191], off nt
	global_load_dword v124, v[196:197], off nt
	global_load_dword v125, v[194:195], off nt
	global_load_dword v126, v[200:201], off nt
	global_load_dword v127, v[198:199], off nt
	global_load_dword v128, v[204:205], off nt
	global_load_dword v129, v[202:203], off nt
	global_load_dword v130, v[208:209], off nt
	global_load_dword v131, v[206:207], off nt
	global_load_dword v132, v[212:213], off nt
	global_load_dword v133, v[210:211], off nt
	global_load_dword v134, v[216:217], off nt
	global_load_dword v135, v[214:215], off nt
	s_add_i32 s5, s5, 16
	s_add_i32 s6, s6, 16
	s_mov_b32 s7, 0
	v_mad_u64_u32 v[186:187], s[8:9], v11, s1, v[6:7]
	v_mad_u64_u32 v[188:189], s[8:9], v9, s1, v[6:7]
	v_mad_u64_u32 v[190:191], s[8:9], v71, s1, v[6:7]
	v_mad_u64_u32 v[192:193], s[8:9], v70, s1, v[6:7]
	v_mad_u64_u32 v[194:195], s[8:9], v73, s1, v[6:7]
	v_mad_u64_u32 v[196:197], s[8:9], v72, s1, v[6:7]
	v_mad_u64_u32 v[198:199], s[8:9], v75, s1, v[6:7]
	v_mad_u64_u32 v[200:201], s[8:9], v74, s1, v[6:7]
	v_mad_u64_u32 v[202:203], s[8:9], v77, s1, v[6:7]
	v_mad_u64_u32 v[204:205], s[8:9], v76, s1, v[6:7]
	v_mad_u64_u32 v[206:207], s[8:9], v79, s1, v[6:7]
	v_mad_u64_u32 v[208:209], s[8:9], v78, s1, v[6:7]
	v_mad_u64_u32 v[210:211], s[8:9], v81, s1, v[6:7]
	v_mad_u64_u32 v[212:213], s[8:9], v80, s1, v[6:7]
	v_mad_u64_u32 v[214:215], s[8:9], v83, s1, v[6:7]
	v_mad_u64_u32 v[216:217], s[8:9], v82, s1, v[6:7]
	s_waitcnt vmcnt(31)
	ds_write_b32 v38, v17
	s_waitcnt vmcnt(30)
	ds_write_b32 v40, v37
	s_waitcnt vmcnt(29)
	ds_write_b32 v42, v84
	s_waitcnt vmcnt(28)
	ds_write_b32 v44, v85
	s_waitcnt vmcnt(27)
	ds_write_b32 v46, v86
	s_waitcnt vmcnt(26)
	ds_write_b32 v48, v87
	s_waitcnt vmcnt(25)
	ds_write_b32 v50, v88
	s_waitcnt vmcnt(24)
	ds_write_b32 v52, v89
	s_waitcnt vmcnt(23)
	ds_write_b32 v54, v90
	s_waitcnt vmcnt(22)
	ds_write_b32 v56, v91
	s_waitcnt vmcnt(21)
	ds_write_b32 v58, v92
	s_waitcnt vmcnt(20)
	ds_write_b32 v60, v93
	s_waitcnt vmcnt(19)
	ds_write_b32 v62, v94
	s_waitcnt vmcnt(18)
	ds_write_b32 v64, v95
	s_waitcnt vmcnt(17)
	ds_write_b32 v66, v96
	s_waitcnt vmcnt(16)
	ds_write_b32 v68, v97
	s_waitcnt vmcnt(15)
	ds_write_b32 v186, v120
	s_waitcnt vmcnt(14)
	ds_write_b32 v188, v121
	s_waitcnt vmcnt(13)
	ds_write_b32 v190, v122
	s_waitcnt vmcnt(12)
	ds_write_b32 v192, v123
	s_waitcnt vmcnt(11)
	ds_write_b32 v194, v124
	s_waitcnt vmcnt(10)
	ds_write_b32 v196, v125
	s_waitcnt vmcnt(9)
	ds_write_b32 v198, v126
	s_waitcnt vmcnt(8)
	ds_write_b32 v200, v127
	s_waitcnt vmcnt(7)
	ds_write_b32 v202, v128
	s_waitcnt vmcnt(6)
	ds_write_b32 v204, v129
	s_waitcnt vmcnt(5)
	ds_write_b32 v206, v130
	s_waitcnt vmcnt(4)
	ds_write_b32 v208, v131
	s_waitcnt vmcnt(3)
	ds_write_b32 v210, v132
	s_waitcnt vmcnt(2)
	ds_write_b32 v212, v133
	s_waitcnt vmcnt(1)
	ds_write_b32 v214, v134
	s_waitcnt vmcnt(0)
	ds_write_b32 v216, v135
	s_waitcnt lgkmcnt(0)
	v_ashrrev_i32_e32 v17, 31, v16
	v_lshl_add_u64 v[2:3], v[16:17], 1, v[14:15]
	ds_read2_b32 v[16:17], v20 offset0:33 offset1:41
	ds_read2_b32 v[18:19], v20 offset1:8
	ds_read2_b32 v[38:39], v20 offset0:66 offset1:74
	ds_read2_b32 v[40:41], v20 offset0:99 offset1:107
	ds_read2_b32 v[42:43], v20 offset0:132 offset1:140
	ds_read2_b32 v[44:45], v20 offset0:165 offset1:173
	ds_read2_b32 v[46:47], v20 offset0:198 offset1:206
	ds_read2_b32 v[48:49], v20 offset0:231 offset1:239
	v_or_b32_e32 v7, v4, v185
	v_ashrrev_i32_e32 v9, 31, v4
	v_mov_b32_e32 v11, v5
	v_mul_lo_u32 v9, v9, v36
	v_mad_u64_u32 v[50:51], s[6:7], v7, v36, 0
	v_lshl_add_u64 v[2:3], v[2:3], 0, v[10:11]
	v_add_u32_e32 v51, v51, v9
	s_waitcnt lgkmcnt(6)
	v_cvt_pk_bf16_f32 v12, v18, v16
	s_waitcnt lgkmcnt(4)
	v_cvt_pk_bf16_f32 v13, v38, v40
	s_waitcnt lgkmcnt(2)
	v_cvt_pk_bf16_f32 v14, v42, v44
	s_waitcnt lgkmcnt(0)
	v_cvt_pk_bf16_f32 v15, v46, v48
	v_lshl_add_u64 v[50:51], v[50:51], 1, v[2:3]
	global_store_dwordx4 v[50:51], v[12:15], off sc1
	v_or_b32_e32 v7, v4, v21
	s_add_i32 s5, s0, 0x80
	v_cvt_pk_bf16_f32 v12, v19, v17
	v_cvt_pk_bf16_f32 v13, v39, v41
	v_cvt_pk_bf16_f32 v14, v43, v45
	v_cvt_pk_bf16_f32 v15, v47, v49
	v_mad_u64_u32 v[16:17], s[6:7], v7, v36, 0
	ds_read2_b32 v[18:19], v20 offset0:16 offset1:24
	ds_read2_b32 v[38:39], v20 offset0:49 offset1:57
	ds_read2_b32 v[40:41], v20 offset0:82 offset1:90
	ds_read2_b32 v[42:43], v20 offset0:115 offset1:123
	ds_read2_b32 v[44:45], v20 offset0:148 offset1:156
	ds_read2_b32 v[46:47], v20 offset0:181 offset1:189
	ds_read2_b32 v[48:49], v20 offset0:214 offset1:222
	ds_read2_b32 v[50:51], v20 offset0:247 offset1:255
	v_add_u32_e32 v17, v17, v9
	v_lshl_add_u64 v[16:17], v[16:17], 1, v[2:3]
	v_or_b32_e32 v7, v4, v22
	global_store_dwordx4 v[16:17], v[12:15], off sc1
	v_mad_u64_u32 v[16:17], s[6:7], v7, v36, 0
	v_add_u32_e32 v17, v17, v9
	s_waitcnt lgkmcnt(6)
	v_cvt_pk_bf16_f32 v12, v18, v38
	s_waitcnt lgkmcnt(4)
	v_cvt_pk_bf16_f32 v13, v40, v42
	s_waitcnt lgkmcnt(2)
	v_cvt_pk_bf16_f32 v14, v44, v46
	s_waitcnt lgkmcnt(0)
	v_cvt_pk_bf16_f32 v15, v48, v50
	v_lshl_add_u64 v[16:17], v[16:17], 1, v[2:3]
	v_or_b32_e32 v4, v4, v23
	global_store_dwordx4 v[16:17], v[12:15], off sc1
	v_mad_u64_u32 v[16:17], s[6:7], v4, v36, 0
	v_add_u32_e32 v17, v17, v9
	v_cvt_pk_bf16_f32 v12, v19, v39
	v_cvt_pk_bf16_f32 v13, v41, v43
	v_cvt_pk_bf16_f32 v14, v45, v47
	v_cvt_pk_bf16_f32 v15, v49, v51
	v_lshl_add_u64 v[2:3], v[16:17], 1, v[2:3]
	global_store_dwordx4 v[2:3], v[12:15], off sc1
	s_waitcnt lgkmcnt(0)
	s_cmpk_gt_i32 s0, 0x38f
	s_mov_b32 s0, s5
	s_cbranch_scc0 .Lgu0h_BB0_1019

.LBB0_1032:
	s_lshl_b32 s8, s6, 1
	s_lshl_b32 s9, s5, 1
	v_or_b32_e32 v9, s8, v1
	v_or_b32_e32 v11, s9, v0
	s_add_i32 s10, s8, 4
	s_add_i32 s11, s9, 4
	s_add_i32 s12, s8, 8
	s_add_i32 s13, s9, 8
	s_add_i32 s14, s8, 12
	s_add_i32 s15, s9, 12
	s_add_i32 s16, s8, 16
	s_add_i32 s17, s9, 16
	s_add_i32 s18, s8, 20
	s_add_i32 s19, s9, 20
	s_add_i32 s20, s8, 24
	s_add_i32 s21, s9, 24
	s_add_i32 s8, s8, 28
	s_add_i32 s9, s9, 28
	v_add_u32_e32 v17, v9, v7
	v_add_u32_e32 v37, v11, v16
	v_or_b32_e32 v70, s10, v1
	v_or_b32_e32 v71, s11, v0
	v_or_b32_e32 v72, s12, v1
	v_or_b32_e32 v73, s13, v0
	v_or_b32_e32 v74, s14, v1
	v_or_b32_e32 v75, s15, v0
	v_or_b32_e32 v76, s16, v1
	v_or_b32_e32 v77, s17, v0
	v_or_b32_e32 v78, s18, v1
	v_or_b32_e32 v79, s19, v0
	v_or_b32_e32 v80, s20, v1
	v_or_b32_e32 v81, s21, v0
	v_or_b32_e32 v82, s8, v1
	v_or_b32_e32 v83, s9, v0
	v_ashrrev_i32_e32 v42, 31, v37
	v_ashrrev_i32_e32 v43, 31, v17
	v_mul_lo_u32 v84, v3, v17
	v_mad_u64_u32 v[38:39], s[8:9], v2, v17, 0
	v_mul_lo_u32 v17, v13, v37
	v_mad_u64_u32 v[40:41], s[8:9], v12, v37, 0
	v_add_u32_e32 v37, v70, v7
	v_add_u32_e32 v44, v71, v16
	v_add_u32_e32 v46, v72, v7
	v_add_u32_e32 v48, v73, v16
	v_add_u32_e32 v50, v74, v7
	v_add_u32_e32 v52, v75, v16
	v_add_u32_e32 v54, v76, v7
	v_add_u32_e32 v56, v77, v16
	v_add_u32_e32 v58, v78, v7
	v_add_u32_e32 v60, v79, v16
	v_add_u32_e32 v62, v80, v7
	v_add_u32_e32 v64, v81, v16
	v_add_u32_e32 v66, v82, v7
	v_add_u32_e32 v68, v83, v16
	v_mul_lo_u32 v85, v2, v43
	v_mul_lo_u32 v86, v12, v42
	v_ashrrev_i32_e32 v87, 31, v44
	v_ashrrev_i32_e32 v88, 31, v37
	v_ashrrev_i32_e32 v90, 31, v48
	v_ashrrev_i32_e32 v91, 31, v46
	v_ashrrev_i32_e32 v94, 31, v52
	v_ashrrev_i32_e32 v95, 31, v50
	v_ashrrev_i32_e32 v98, 31, v56
	v_ashrrev_i32_e32 v99, 31, v54
	v_ashrrev_i32_e32 v102, 31, v60
	v_ashrrev_i32_e32 v103, 31, v58
	v_ashrrev_i32_e32 v106, 31, v64
	v_ashrrev_i32_e32 v107, 31, v62
	v_ashrrev_i32_e32 v110, 31, v68
	v_ashrrev_i32_e32 v111, 31, v66
	v_mul_lo_u32 v89, v3, v37
	v_mad_u64_u32 v[42:43], s[8:9], v2, v37, 0
	v_mul_lo_u32 v37, v13, v44
	v_mad_u64_u32 v[44:45], s[8:9], v12, v44, 0
	v_mul_lo_u32 v92, v3, v46
	v_mad_u64_u32 v[46:47], s[8:9], v2, v46, 0
	v_mul_lo_u32 v93, v13, v48
	v_mad_u64_u32 v[48:49], s[8:9], v12, v48, 0
	v_mul_lo_u32 v96, v3, v50
	v_mad_u64_u32 v[50:51], s[8:9], v2, v50, 0
	v_mul_lo_u32 v97, v13, v52
	v_mad_u64_u32 v[52:53], s[8:9], v12, v52, 0
	v_mul_lo_u32 v100, v3, v54
	v_mad_u64_u32 v[54:55], s[8:9], v2, v54, 0
	v_mul_lo_u32 v101, v13, v56
	v_mad_u64_u32 v[56:57], s[8:9], v12, v56, 0
	v_mul_lo_u32 v104, v3, v58
	v_mad_u64_u32 v[58:59], s[8:9], v2, v58, 0
	v_mul_lo_u32 v105, v13, v60
	v_mad_u64_u32 v[60:61], s[8:9], v12, v60, 0
	v_mul_lo_u32 v108, v3, v62
	v_mad_u64_u32 v[62:63], s[8:9], v2, v62, 0
	v_mul_lo_u32 v109, v13, v64
	v_mad_u64_u32 v[64:65], s[8:9], v12, v64, 0
	v_mul_lo_u32 v112, v3, v66
	v_mad_u64_u32 v[66:67], s[8:9], v2, v66, 0
	v_mul_lo_u32 v113, v13, v68
	v_mad_u64_u32 v[68:69], s[8:9], v12, v68, 0
	v_add3_u32 v39, v39, v85, v84
	v_add3_u32 v41, v41, v86, v17
	v_mul_lo_u32 v17, v2, v88
	v_mul_lo_u32 v84, v12, v87
	v_mul_lo_u32 v85, v2, v91
	v_mul_lo_u32 v86, v12, v90
	v_mul_lo_u32 v87, v2, v95
	v_mul_lo_u32 v88, v12, v94
	v_mul_lo_u32 v90, v2, v99
	v_mul_lo_u32 v91, v12, v98
	v_mul_lo_u32 v94, v2, v103
	v_mul_lo_u32 v95, v12, v102
	v_mul_lo_u32 v98, v2, v107
	v_mul_lo_u32 v99, v12, v106
	v_mul_lo_u32 v102, v2, v111
	v_mul_lo_u32 v103, v12, v110
	v_lshl_add_u64 v[40:41], v[40:41], 2, v[18:19]
	v_add3_u32 v43, v43, v17, v89
	v_add3_u32 v45, v45, v84, v37
	v_add3_u32 v47, v47, v85, v92
	v_add3_u32 v49, v49, v86, v93
	v_add3_u32 v51, v51, v87, v96
	v_add3_u32 v53, v53, v88, v97
	v_add3_u32 v55, v55, v90, v100
	v_add3_u32 v57, v57, v91, v101
	v_add3_u32 v59, v59, v94, v104
	v_add3_u32 v61, v61, v95, v105
	v_add3_u32 v63, v63, v98, v108
	v_add3_u32 v65, v65, v99, v109
	v_add3_u32 v67, v67, v102, v112
	v_add3_u32 v69, v69, v103, v113
	v_lshl_add_u64 v[38:39], v[38:39], 2, v[18:19]
	v_lshl_add_u64 v[44:45], v[44:45], 2, v[18:19]
	v_lshl_add_u64 v[42:43], v[42:43], 2, v[18:19]
	v_lshl_add_u64 v[48:49], v[48:49], 2, v[18:19]
	v_lshl_add_u64 v[46:47], v[46:47], 2, v[18:19]
	v_lshl_add_u64 v[52:53], v[52:53], 2, v[18:19]
	v_lshl_add_u64 v[50:51], v[50:51], 2, v[18:19]
	v_lshl_add_u64 v[56:57], v[56:57], 2, v[18:19]
	v_lshl_add_u64 v[54:55], v[54:55], 2, v[18:19]
	v_lshl_add_u64 v[60:61], v[60:61], 2, v[18:19]
	v_lshl_add_u64 v[58:59], v[58:59], 2, v[18:19]
	v_lshl_add_u64 v[64:65], v[64:65], 2, v[18:19]
	v_lshl_add_u64 v[62:63], v[62:63], 2, v[18:19]
	v_lshl_add_u64 v[68:69], v[68:69], 2, v[18:19]
	v_lshl_add_u64 v[66:67], v[66:67], 2, v[18:19]
	global_load_dword v17, v[40:41], off nt
	global_load_dword v37, v[38:39], off nt
	global_load_dword v84, v[44:45], off nt
	global_load_dword v85, v[42:43], off nt
	global_load_dword v86, v[48:49], off nt
	global_load_dword v87, v[46:47], off nt
	global_load_dword v88, v[52:53], off nt
	global_load_dword v89, v[50:51], off nt
	global_load_dword v90, v[56:57], off nt
	global_load_dword v91, v[54:55], off nt
	global_load_dword v92, v[60:61], off nt
	global_load_dword v93, v[58:59], off nt
	global_load_dword v94, v[64:65], off nt
	global_load_dword v95, v[62:63], off nt
	global_load_dword v96, v[68:69], off nt
	global_load_dword v97, v[66:67], off nt
	s_add_i32 s5, s5, 16
	s_add_i32 s6, s6, 16
	v_mad_u64_u32 v[38:39], s[8:9], v11, s1, v[6:7]
	v_mad_u64_u32 v[40:41], s[8:9], v9, s1, v[6:7]
	v_mad_u64_u32 v[42:43], s[8:9], v71, s1, v[6:7]
	v_mad_u64_u32 v[44:45], s[8:9], v70, s1, v[6:7]
	v_mad_u64_u32 v[46:47], s[8:9], v73, s1, v[6:7]
	v_mad_u64_u32 v[48:49], s[8:9], v72, s1, v[6:7]
	v_mad_u64_u32 v[50:51], s[8:9], v75, s1, v[6:7]
	v_mad_u64_u32 v[52:53], s[8:9], v74, s1, v[6:7]
	v_mad_u64_u32 v[54:55], s[8:9], v77, s1, v[6:7]
	v_mad_u64_u32 v[56:57], s[8:9], v76, s1, v[6:7]
	v_mad_u64_u32 v[58:59], s[8:9], v79, s1, v[6:7]
	v_mad_u64_u32 v[60:61], s[8:9], v78, s1, v[6:7]
	v_mad_u64_u32 v[62:63], s[8:9], v81, s1, v[6:7]
	v_mad_u64_u32 v[64:65], s[8:9], v80, s1, v[6:7]
	v_mad_u64_u32 v[66:67], s[8:9], v83, s1, v[6:7]
	v_mad_u64_u32 v[68:69], s[8:9], v82, s1, v[6:7]
	s_lshl_b32 s8, s6, 1
	s_lshl_b32 s9, s5, 1
	v_or_b32_e32 v9, s8, v1
	v_or_b32_e32 v11, s9, v0
	s_add_i32 s10, s8, 4
	s_add_i32 s11, s9, 4
	s_add_i32 s12, s8, 8
	s_add_i32 s13, s9, 8
	s_add_i32 s14, s8, 12
	s_add_i32 s15, s9, 12
	s_add_i32 s16, s8, 16
	s_add_i32 s17, s9, 16
	s_add_i32 s18, s8, 20
	s_add_i32 s19, s9, 20
	s_add_i32 s20, s8, 24
	s_add_i32 s21, s9, 24
	s_add_i32 s8, s8, 28
	s_add_i32 s9, s9, 28
	v_add_u32_e32 v120, v9, v7
	v_add_u32_e32 v121, v11, v16
	v_or_b32_e32 v70, s10, v1
	v_or_b32_e32 v71, s11, v0
	v_or_b32_e32 v72, s12, v1
	v_or_b32_e32 v73, s13, v0
	v_or_b32_e32 v74, s14, v1
	v_or_b32_e32 v75, s15, v0
	v_or_b32_e32 v76, s16, v1
	v_or_b32_e32 v77, s17, v0
	v_or_b32_e32 v78, s18, v1
	v_or_b32_e32 v79, s19, v0
	v_or_b32_e32 v80, s20, v1
	v_or_b32_e32 v81, s21, v0
	v_or_b32_e32 v82, s8, v1
	v_or_b32_e32 v83, s9, v0
	v_ashrrev_i32_e32 v190, 31, v121
	v_ashrrev_i32_e32 v191, 31, v120
	v_mul_lo_u32 v122, v3, v120
	v_mad_u64_u32 v[186:187], s[8:9], v2, v120, 0
	v_mul_lo_u32 v120, v13, v121
	v_mad_u64_u32 v[188:189], s[8:9], v12, v121, 0
	v_add_u32_e32 v121, v70, v7
	v_add_u32_e32 v192, v71, v16
	v_add_u32_e32 v194, v72, v7
	v_add_u32_e32 v196, v73, v16
	v_add_u32_e32 v198, v74, v7
	v_add_u32_e32 v200, v75, v16
	v_add_u32_e32 v202, v76, v7
	v_add_u32_e32 v204, v77, v16
	v_add_u32_e32 v206, v78, v7
	v_add_u32_e32 v208, v79, v16
	v_add_u32_e32 v210, v80, v7
	v_add_u32_e32 v212, v81, v16
	v_add_u32_e32 v214, v82, v7
	v_add_u32_e32 v216, v83, v16
	v_mul_lo_u32 v123, v2, v191
	v_mul_lo_u32 v124, v12, v190
	v_ashrrev_i32_e32 v125, 31, v192
	v_ashrrev_i32_e32 v126, 31, v121
	v_ashrrev_i32_e32 v128, 31, v196
	v_ashrrev_i32_e32 v129, 31, v194
	v_ashrrev_i32_e32 v132, 31, v200
	v_ashrrev_i32_e32 v133, 31, v198
	v_ashrrev_i32_e32 v98, 31, v204
	v_ashrrev_i32_e32 v99, 31, v202
	v_ashrrev_i32_e32 v102, 31, v208
	v_ashrrev_i32_e32 v103, 31, v206
	v_ashrrev_i32_e32 v106, 31, v212
	v_ashrrev_i32_e32 v107, 31, v210
	v_ashrrev_i32_e32 v110, 31, v216
	v_ashrrev_i32_e32 v111, 31, v214
	v_mul_lo_u32 v127, v3, v121
	v_mad_u64_u32 v[190:191], s[8:9], v2, v121, 0
	v_mul_lo_u32 v121, v13, v192
	v_mad_u64_u32 v[192:193], s[8:9], v12, v192, 0
	v_mul_lo_u32 v130, v3, v194
	v_mad_u64_u32 v[194:195], s[8:9], v2, v194, 0
	v_mul_lo_u32 v131, v13, v196
	v_mad_u64_u32 v[196:197], s[8:9], v12, v196, 0
	v_mul_lo_u32 v134, v3, v198
	v_mad_u64_u32 v[198:199], s[8:9], v2, v198, 0
	v_mul_lo_u32 v135, v13, v200
	v_mad_u64_u32 v[200:201], s[8:9], v12, v200, 0
	v_mul_lo_u32 v100, v3, v202
	v_mad_u64_u32 v[202:203], s[8:9], v2, v202, 0
	v_mul_lo_u32 v101, v13, v204
	v_mad_u64_u32 v[204:205], s[8:9], v12, v204, 0
	v_mul_lo_u32 v104, v3, v206
	v_mad_u64_u32 v[206:207], s[8:9], v2, v206, 0
	v_mul_lo_u32 v105, v13, v208
	v_mad_u64_u32 v[208:209], s[8:9], v12, v208, 0
	v_mul_lo_u32 v108, v3, v210
	v_mad_u64_u32 v[210:211], s[8:9], v2, v210, 0
	v_mul_lo_u32 v109, v13, v212
	v_mad_u64_u32 v[212:213], s[8:9], v12, v212, 0
	v_mul_lo_u32 v112, v3, v214
	v_mad_u64_u32 v[214:215], s[8:9], v2, v214, 0
	v_mul_lo_u32 v113, v13, v216
	v_mad_u64_u32 v[216:217], s[8:9], v12, v216, 0
	v_add3_u32 v187, v187, v123, v122
	v_add3_u32 v189, v189, v124, v120
	v_mul_lo_u32 v120, v2, v126
	v_mul_lo_u32 v122, v12, v125
	v_mul_lo_u32 v123, v2, v129
	v_mul_lo_u32 v124, v12, v128
	v_mul_lo_u32 v125, v2, v133
	v_mul_lo_u32 v126, v12, v132
	v_mul_lo_u32 v128, v2, v99
	v_mul_lo_u32 v129, v12, v98
	v_mul_lo_u32 v132, v2, v103
	v_mul_lo_u32 v133, v12, v102
	v_mul_lo_u32 v98, v2, v107
	v_mul_lo_u32 v99, v12, v106
	v_mul_lo_u32 v102, v2, v111
	v_mul_lo_u32 v103, v12, v110
	v_lshl_add_u64 v[188:189], v[188:189], 2, v[18:19]
	v_add3_u32 v191, v191, v120, v127
	v_add3_u32 v193, v193, v122, v121
	v_add3_u32 v195, v195, v123, v130
	v_add3_u32 v197, v197, v124, v131
	v_add3_u32 v199, v199, v125, v134
	v_add3_u32 v201, v201, v126, v135
	v_add3_u32 v203, v203, v128, v100
	v_add3_u32 v205, v205, v129, v101
	v_add3_u32 v207, v207, v132, v104
	v_add3_u32 v209, v209, v133, v105
	v_add3_u32 v211, v211, v98, v108
	v_add3_u32 v213, v213, v99, v109
	v_add3_u32 v215, v215, v102, v112
	v_add3_u32 v217, v217, v103, v113
	v_lshl_add_u64 v[186:187], v[186:187], 2, v[18:19]
	v_lshl_add_u64 v[192:193], v[192:193], 2, v[18:19]
	v_lshl_add_u64 v[190:191], v[190:191], 2, v[18:19]
	v_lshl_add_u64 v[196:197], v[196:197], 2, v[18:19]
	v_lshl_add_u64 v[194:195], v[194:195], 2, v[18:19]
	v_lshl_add_u64 v[200:201], v[200:201], 2, v[18:19]
	v_lshl_add_u64 v[198:199], v[198:199], 2, v[18:19]
	v_lshl_add_u64 v[204:205], v[204:205], 2, v[18:19]
	v_lshl_add_u64 v[202:203], v[202:203], 2, v[18:19]
	v_lshl_add_u64 v[208:209], v[208:209], 2, v[18:19]
	v_lshl_add_u64 v[206:207], v[206:207], 2, v[18:19]
	v_lshl_add_u64 v[212:213], v[212:213], 2, v[18:19]
	v_lshl_add_u64 v[210:211], v[210:211], 2, v[18:19]
	v_lshl_add_u64 v[216:217], v[216:217], 2, v[18:19]
	v_lshl_add_u64 v[214:215], v[214:215], 2, v[18:19]
	global_load_dword v120, v[188:189], off nt
	global_load_dword v121, v[186:187], off nt
	global_load_dword v122, v[192:193], off nt
	global_load_dword v123, v[190:191], off nt
	global_load_dword v124, v[196:197], off nt
	global_load_dword v125, v[194:195], off nt
	global_load_dword v126, v[200:201], off nt
	global_load_dword v127, v[198:199], off nt
	global_load_dword v128, v[204:205], off nt
	global_load_dword v129, v[202:203], off nt
	global_load_dword v130, v[208:209], off nt
	global_load_dword v131, v[206:207], off nt
	global_load_dword v132, v[212:213], off nt
	global_load_dword v133, v[210:211], off nt
	global_load_dword v134, v[216:217], off nt
	global_load_dword v135, v[214:215], off nt
	s_add_i32 s5, s5, 16
	s_add_i32 s6, s6, 16
	s_mov_b32 s7, 0
	v_mad_u64_u32 v[186:187], s[8:9], v11, s1, v[6:7]
	v_mad_u64_u32 v[188:189], s[8:9], v9, s1, v[6:7]
	v_mad_u64_u32 v[190:191], s[8:9], v71, s1, v[6:7]
	v_mad_u64_u32 v[192:193], s[8:9], v70, s1, v[6:7]
	v_mad_u64_u32 v[194:195], s[8:9], v73, s1, v[6:7]
	v_mad_u64_u32 v[196:197], s[8:9], v72, s1, v[6:7]
	v_mad_u64_u32 v[198:199], s[8:9], v75, s1, v[6:7]
	v_mad_u64_u32 v[200:201], s[8:9], v74, s1, v[6:7]
	v_mad_u64_u32 v[202:203], s[8:9], v77, s1, v[6:7]
	v_mad_u64_u32 v[204:205], s[8:9], v76, s1, v[6:7]
	v_mad_u64_u32 v[206:207], s[8:9], v79, s1, v[6:7]
	v_mad_u64_u32 v[208:209], s[8:9], v78, s1, v[6:7]
	v_mad_u64_u32 v[210:211], s[8:9], v81, s1, v[6:7]
	v_mad_u64_u32 v[212:213], s[8:9], v80, s1, v[6:7]
	v_mad_u64_u32 v[214:215], s[8:9], v83, s1, v[6:7]
	v_mad_u64_u32 v[216:217], s[8:9], v82, s1, v[6:7]
	s_waitcnt vmcnt(31)
	ds_write_b32 v38, v17
	s_waitcnt vmcnt(30)
	ds_write_b32 v40, v37
	s_waitcnt vmcnt(29)
	ds_write_b32 v42, v84
	s_waitcnt vmcnt(28)
	ds_write_b32 v44, v85
	s_waitcnt vmcnt(27)
	ds_write_b32 v46, v86
	s_waitcnt vmcnt(26)
	ds_write_b32 v48, v87
	s_waitcnt vmcnt(25)
	ds_write_b32 v50, v88
	s_waitcnt vmcnt(24)
	ds_write_b32 v52, v89
	s_waitcnt vmcnt(23)
	ds_write_b32 v54, v90
	s_waitcnt vmcnt(22)
	ds_write_b32 v56, v91
	s_waitcnt vmcnt(21)
	ds_write_b32 v58, v92
	s_waitcnt vmcnt(20)
	ds_write_b32 v60, v93
	s_waitcnt vmcnt(19)
	ds_write_b32 v62, v94
	s_waitcnt vmcnt(18)
	ds_write_b32 v64, v95
	s_waitcnt vmcnt(17)
	ds_write_b32 v66, v96
	s_waitcnt vmcnt(16)
	ds_write_b32 v68, v97
	s_waitcnt vmcnt(15)
	ds_write_b32 v186, v120
	s_waitcnt vmcnt(14)
	ds_write_b32 v188, v121
	s_waitcnt vmcnt(13)
	ds_write_b32 v190, v122
	s_waitcnt vmcnt(12)
	ds_write_b32 v192, v123
	s_waitcnt vmcnt(11)
	ds_write_b32 v194, v124
	s_waitcnt vmcnt(10)
	ds_write_b32 v196, v125
	s_waitcnt vmcnt(9)
	ds_write_b32 v198, v126
	s_waitcnt vmcnt(8)
	ds_write_b32 v200, v127
	s_waitcnt vmcnt(7)
	ds_write_b32 v202, v128
	s_waitcnt vmcnt(6)
	ds_write_b32 v204, v129
	s_waitcnt vmcnt(5)
	ds_write_b32 v206, v130
	s_waitcnt vmcnt(4)
	ds_write_b32 v208, v131
	s_waitcnt vmcnt(3)
	ds_write_b32 v210, v132
	s_waitcnt vmcnt(2)
	ds_write_b32 v212, v133
	s_waitcnt vmcnt(1)
	ds_write_b32 v214, v134
	s_waitcnt vmcnt(0)
	ds_write_b32 v216, v135
	s_waitcnt lgkmcnt(0)
	v_ashrrev_i32_e32 v17, 31, v16
	v_lshl_add_u64 v[2:3], v[16:17], 1, v[14:15]
	ds_read2_b32 v[16:17], v20 offset0:33 offset1:41
	ds_read2_b32 v[18:19], v20 offset1:8
	ds_read2_b32 v[38:39], v20 offset0:66 offset1:74
	ds_read2_b32 v[40:41], v20 offset0:99 offset1:107
	ds_read2_b32 v[42:43], v20 offset0:132 offset1:140
	ds_read2_b32 v[44:45], v20 offset0:165 offset1:173
	ds_read2_b32 v[46:47], v20 offset0:198 offset1:206
	ds_read2_b32 v[48:49], v20 offset0:231 offset1:239
	v_or_b32_e32 v7, v4, v185
	v_ashrrev_i32_e32 v9, 31, v4
	v_mov_b32_e32 v11, v5
	v_mul_lo_u32 v9, v9, v36
	v_mad_u64_u32 v[50:51], s[6:7], v7, v36, 0
	v_lshl_add_u64 v[2:3], v[2:3], 0, v[10:11]
	v_add_u32_e32 v51, v51, v9
	s_waitcnt lgkmcnt(6)
	v_cvt_pk_bf16_f32 v12, v18, v16
	s_waitcnt lgkmcnt(4)
	v_cvt_pk_bf16_f32 v13, v38, v40
	s_waitcnt lgkmcnt(2)
	v_cvt_pk_bf16_f32 v14, v42, v44
	s_waitcnt lgkmcnt(0)
	v_cvt_pk_bf16_f32 v15, v46, v48
	v_lshl_add_u64 v[50:51], v[50:51], 1, v[2:3]
	global_store_dwordx4 v[50:51], v[12:15], off sc1
	v_or_b32_e32 v7, v4, v21
	s_add_i32 s5, s0, 0x80
	v_cvt_pk_bf16_f32 v12, v19, v17
	v_cvt_pk_bf16_f32 v13, v39, v41
	v_cvt_pk_bf16_f32 v14, v43, v45
	v_cvt_pk_bf16_f32 v15, v47, v49
	v_mad_u64_u32 v[16:17], s[6:7], v7, v36, 0
	ds_read2_b32 v[18:19], v20 offset0:16 offset1:24
	ds_read2_b32 v[38:39], v20 offset0:49 offset1:57
	ds_read2_b32 v[40:41], v20 offset0:82 offset1:90
	ds_read2_b32 v[42:43], v20 offset0:115 offset1:123
	ds_read2_b32 v[44:45], v20 offset0:148 offset1:156
	ds_read2_b32 v[46:47], v20 offset0:181 offset1:189
	ds_read2_b32 v[48:49], v20 offset0:214 offset1:222
	ds_read2_b32 v[50:51], v20 offset0:247 offset1:255
	v_add_u32_e32 v17, v17, v9
	v_lshl_add_u64 v[16:17], v[16:17], 1, v[2:3]
	v_or_b32_e32 v7, v4, v22
	global_store_dwordx4 v[16:17], v[12:15], off sc1
	v_mad_u64_u32 v[16:17], s[6:7], v7, v36, 0
	v_add_u32_e32 v17, v17, v9
	s_waitcnt lgkmcnt(6)
	v_cvt_pk_bf16_f32 v12, v18, v38
	s_waitcnt lgkmcnt(4)
	v_cvt_pk_bf16_f32 v13, v40, v42
	s_waitcnt lgkmcnt(2)
	v_cvt_pk_bf16_f32 v14, v44, v46
	s_waitcnt lgkmcnt(0)
	v_cvt_pk_bf16_f32 v15, v48, v50
	v_lshl_add_u64 v[16:17], v[16:17], 1, v[2:3]
	v_or_b32_e32 v4, v4, v23
	global_store_dwordx4 v[16:17], v[12:15], off sc1
	v_mad_u64_u32 v[16:17], s[6:7], v4, v36, 0
	v_add_u32_e32 v17, v17, v9
	v_cvt_pk_bf16_f32 v12, v19, v39
	v_cvt_pk_bf16_f32 v13, v41, v43
	v_cvt_pk_bf16_f32 v14, v45, v47
	v_cvt_pk_bf16_f32 v15, v49, v51
	v_lshl_add_u64 v[2:3], v[16:17], 1, v[2:3]
	global_store_dwordx4 v[2:3], v[12:15], off sc1
	s_waitcnt lgkmcnt(0)
	s_cmpk_gt_i32 s0, 0x53f
	s_mov_b32 s0, s5
	s_cbranch_scc0 .LBB0_1019
